# v35 + job_wconv matrix lookup from the module's fixed tile counts (19 dependent scalar loads removed per tile)
# baseline (speedup 1.0000x reference)
.LBB0_35:
	s_and_b64 vcc, exec, s[6:7]
	s_cbranch_vccz .LBB0_87
	s_add_i32 s52, s89, 0xfffffe80
	s_mov_b32 s8, 0
	s_cmpk_ge_i32 s52, 0x80
	s_cselect_b32 s8, 1, s8
	s_cmpk_ge_i32 s52, 0x100
	s_cselect_b32 s8, 2, s8
	s_cmpk_ge_i32 s52, 0x300
	s_cselect_b32 s8, 3, s8
	s_cmpk_ge_i32 s52, 0x500
	s_cselect_b32 s8, 4, s8
	s_cmpk_ge_i32 s52, 0x700
	s_cselect_b32 s8, 5, s8
	s_cmpk_ge_i32 s52, 0x900
	s_cselect_b32 s8, 6, s8
	s_cmpk_ge_i32 s52, 0xb00
	s_cselect_b32 s8, 7, s8
	s_cmpk_ge_i32 s52, 0xd00
	s_cselect_b32 s8, 8, s8
	s_cmpk_ge_i32 s52, 0xf00
	s_cselect_b32 s8, 9, s8
	s_cmpk_ge_i32 s52, 0x1100
	s_cselect_b32 s8, 10, s8
	s_cmpk_ge_i32 s52, 0x1280
	s_cselect_b32 s8, 11, s8
	s_cmpk_ge_i32 s52, 0x1400
	s_cselect_b32 s8, 12, s8
	s_cmpk_ge_i32 s52, 0x1480
	s_cselect_b32 s8, 13, s8
	s_cmpk_ge_i32 s52, 0x1500
	s_cselect_b32 s8, 14, s8
	s_cmpk_ge_i32 s52, 0x15a0
	s_cselect_b32 s8, 15, s8
	s_cmpk_ge_i32 s52, 0x1640
	s_cselect_b32 s8, 16, s8
	s_cmpk_ge_i32 s52, 0x1670
	s_cselect_b32 s8, 17, s8
	s_cmpk_ge_i32 s52, 0x16a0
	s_cselect_b32 s8, 18, s8
	s_cmpk_ge_i32 s52, 0x16c0
	s_cselect_b32 s8, 19, s8
	s_mul_i32 s7, s8, 48
	s_mul_hi_u32 s6, s8, 48
	s_add_u32 s50, s0, s7
	s_addc_u32 s51, s1, s6
	s_load_dwordx2 s[6:7], s[50:51], 0x118
	s_load_dwordx4 s[8:11], s[50:51], 0x100
	s_load_dwordx2 s[56:57], s[50:51], 0x124
	s_load_dword s30, s[50:51], 0x12c
	v_mov_b32_e32 v1, v155
	s_waitcnt lgkmcnt(0)
	s_ashr_i32 s53, s6, 7
	s_abs_i32 s54, s53
	v_cvt_f32_u32_e32 v0, s54
	s_sub_i32 s58, 0, s54
	s_sub_i32 s52, s52, s57
	s_abs_i32 s57, s52
	v_rcp_iflag_f32_e32 v0, v0
	s_xor_b32 s55, s52, s53
	s_ashr_i32 s55, s55, 31
	v_mul_f32_e32 v0, 0x4f7ffffe, v0
	v_cvt_u32_f32_e32 v0, v0
	v_ashrrev_i32_e32 v27, 2, v1
	v_readfirstlane_b32 s59, v0
	s_mul_i32 s58, s58, s59
	s_mul_hi_u32 s58, s59, s58
	s_add_i32 s59, s59, s58
	s_mul_hi_u32 s58, s57, s59
	s_mul_i32 s59, s58, s54
	s_sub_i32 s57, s57, s59
	s_add_i32 s90, s58, 1
	s_sub_i32 s59, s57, s54
	s_cmp_ge_u32 s57, s54
	s_cselect_b32 s58, s90, s58
	s_cselect_b32 s57, s59, s57
	s_add_i32 s59, s58, 1
	s_cmp_ge_u32 s57, s54
	s_cselect_b32 s54, s59, s58
	s_xor_b32 s54, s54, s55
	s_sub_i32 s90, s54, s55
	s_mul_i32 s53, s90, s53
	s_sub_i32 s52, s52, s53
	v_and_b32_e32 v0, -16, v27
	v_lshl_add_u32 v26, s52, 7, v0
	s_lshl_b32 s52, s90, 6
	v_mov_b32_e32 v0, v155
	s_cmp_lg_u32 s30, 1
	v_and_or_b32 v28, v0, 63, s52
	s_mov_b64 s[58:59], -1
	s_cbranch_scc0 .LBB0_45
	s_cmp_eq_u32 s56, 0
	s_cbranch_scc1 .LBB0_112
	s_lshr_b32 s58, s90, 1
	v_mad_i64_i32 v[0:1], s[56:57], v26, s7, 0
	s_mul_i32 s56, s58, 0x60
	v_and_b32_e32 v2, 0x7f, v28
	v_lshl_add_u64 v[0:1], v[0:1], 2, s[8:9]
	s_ashr_i32 s57, s56, 31
	v_lshl_add_u64 v[0:1], s[56:57], 2, v[0:1]
	v_lshlrev_b32_e32 v24, 2, v2
	v_cmp_gt_u32_e64 s[52:53], s69, v2
	s_ashr_i32 s55, s7, 31
	s_mov_b32 s54, s7
	v_lshl_add_u64 v[30:31], v[0:1], 0, v[24:25]
	s_cbranch_execnz .LBB0_44
